# prompt stick-breaking tile loop instruction selection: second causal-mask set uses the i < (qpos-kp0) compare form (17 v_add_u32 removed), fmaxf(u,0) folded into one v_max (16 canonicalizing v_max rem
# speedup vs baseline: 1.0134x; 1.0056x over previous
; #define MFMA32(a, b, c) __builtin_amdgcn_mfma_f32_32x32x16_bf16((a), (b), (c), 0, 0, 0)
;     __device__ __forceinline__ void kload(int kt, int ds, KRaw& o) const { o = kfrag(kt, ds); }
;     __device__ __forceinline__ void vload(int kt, int dblk, int s, VRaw& o) const { o = vfrag(kt, dblk, s); }
;     __device__ __forceinline__ void kload(int kt, int ds, KRaw& o) const { const f32x4* p = (const f32x4*)(krow(32 * kt + kap) + 16 * ds + 8 * h); o.a = p[0]; o.b = p[1]; }
;     static __device__ __forceinline__ bf16x8 kpack(const KRaw& x) { return pack8(x.a[0], x.a[1], x.a[2], x.a[3], x.b[0], x.b[1], x.b[2], x.b[3]); }
; template <class Src>
; __device__ __forceinline__ void sb_wave(const Src& src, const bf16* qrow, int kt_hi, int qpos, f32x16 (&O)[2]) {
;     ...
;         typename Src::KRaw kr[4]; typename Src::VRaw vr[4];
; #pragma unroll
;         for (int ds = 0; ds < 4; ++ds) src.kload(kt, ds, kr[ds]);
; #pragma unroll
;         for (int b = 0; b < 2; ++b) { src.vload(kt, b, 0, vr[2 * b]); src.vload(kt, b, 1, vr[2 * b + 1]); }
;         __builtin_amdgcn_sched_barrier(0);
; #pragma unroll
;         for (int ds = 0; ds < 4; ++ds) S = MFMA32(Src::kpack(kr[ds]), qf[ds], S);
;         const int kp0 = 32 * kt + 16 * h;
;         float c[16]; float run = 0.f;
; #pragma unroll
;         for (int i = 15; i >= 0; --i) {
;             const bool valid = (kp0 + i) < qpos;
;             const float u = S[i];
;             const float L = fmaxf(u, 0.f) + __builtin_amdgcn_logf(1.0f + __builtin_amdgcn_exp2f(-fabsf(u)));
;             run += valid ? L : 0.f; c[i] = run;
;         }
;         const float other = __shfl_xor(run, 32);
;         const float off = carry + (h == 0 ? other : 0.f);
;         float a[16];
; #pragma unroll
;         for (int i = 0; i < 16; ++i) { const bool valid = (kp0 + i) < qpos; a[i] = valid ? __builtin_amdgcn_exp2f(S[i] - (c[i] + off)) : 0.f; }
.LBB0_533:
	s_add_i32 s58, s39, 32
	v_add_u32_e32 v32, s58, v109
	v_ashrrev_i32_e32 v33, 31, v32
	v_lshlrev_b64 v[32:33], 10, v[32:33]
	v_lshl_add_u64 v[36:37], v[102:103], 0, v[32:33]
	global_load_dwordx4 v[32:35], v[36:37], off
	global_load_dwordx4 v[112:115], v[36:37], off offset:32
	global_load_dwordx4 v[116:119], v[36:37], off offset:64
	global_load_dwordx4 v[80:83], v[36:37], off offset:96
	v_lshl_add_u64 v[36:37], s[58:59], 1, v[104:105]
	s_mov_b32 s0, 0x101000
	global_load_dwordx4 v[76:79], v[36:37], off
	global_load_dwordx4 v[68:71], v[36:37], off offset:16
	v_add_co_u32_e32 v36, vcc, s0, v36
	s_nop 1
	v_addc_co_u32_e32 v37, vcc, 0, v37, vcc
	global_load_dwordx4 v[72:75], v[36:37], off
	global_load_dwordx4 v[64:67], v[36:37], off offset:16
	s_waitcnt vmcnt(7)
	v_mfma_f32_32x32x16_bf16 v[32:47], v[32:35], v[48:51], 0
	s_waitcnt vmcnt(6)
	v_mfma_f32_32x32x16_bf16 v[32:47], v[112:115], v[52:55], v[32:47]
	v_cmp_lt_i32_e32 vcc, 13, v111
	s_waitcnt vmcnt(5)
	v_mfma_f32_32x32x16_bf16 v[32:47], v[116:119], v[56:59], v[32:47]
	v_cmp_lt_i32_e64 s[36:37], 14, v111
	v_cmp_lt_i32_e64 s[0:1], 12, v111
	v_cmp_lt_i32_e64 s[6:7], 11, v111
	s_waitcnt vmcnt(4)
	v_mfma_f32_32x32x16_bf16 v[32:47], v[80:83], v[60:63], v[32:47]
	v_cmp_lt_i32_e64 s[8:9], 10, v111
	v_cmp_lt_i32_e64 s[10:11], 9, v111
	v_cmp_lt_i32_e64 s[12:13], 8, v111
	v_cmp_lt_i32_e64 s[14:15], 7, v111
	v_cmp_lt_i32_e64 s[16:17], 6, v111
	v_cmp_lt_i32_e64 s[20:21], 5, v111
	v_cmp_lt_i32_e64 s[24:25], 4, v111
	s_nop 4
	v_exp_f32_e64 v81, -|v47|
	v_exp_f32_e64 v83, -|v46|
	v_exp_f32_e64 v130, -|v45|
	v_exp_f32_e64 v132, -|v44|
	v_exp_f32_e64 v134, -|v43|
	v_add_f32_e32 v81, 1.0, v81
	v_add_f32_e32 v83, 1.0, v83
	v_add_f32_e32 v130, 1.0, v130
	v_exp_f32_e64 v137, -|v42|
	v_max_f32_e32 v159, 0, v47
	v_max_f32_e32 v80, 0, v46
	v_max_f32_e32 v82, 0, v45
	v_log_f32_e32 v81, v81
	v_log_f32_e32 v86, v83
	v_log_f32_e32 v83, v130
	v_exp_f32_e64 v140, -|v41|
	v_exp_f32_e64 v142, -|v40|
	v_add_f32_e32 v132, 1.0, v132
	v_exp_f32_e64 v144, -|v39|
	v_add_f32_e32 v134, 1.0, v134
	v_log_f32_e32 v130, v132
	v_exp_f32_e64 v146, -|v38|
	v_add_f32_e32 v137, 1.0, v137
	v_log_f32_e32 v132, v134
	v_add_f32_e32 v81, v159, v81
	v_add_f32_e32 v82, v82, v83
	v_exp_f32_e64 v148, -|v37|
	v_add_f32_e32 v140, 1.0, v140
	v_log_f32_e32 v134, v137
	v_pk_add_f32 v[80:81], v[80:81], v[86:87]
	v_cndmask_b32_e32 v82, 0, v82, vcc
	v_cmp_lt_i32_e32 vcc, 15, v111
	v_exp_f32_e64 v150, -|v36|
	v_max_f32_e32 v131, 0, v44
	v_add_f32_e32 v142, 1.0, v142
	v_log_f32_e32 v137, v140
	v_cndmask_b32_e32 v81, 0, v81, vcc
	v_cndmask_b32_e64 v80, 0, v80, s[36:37]
	v_exp_f32_e64 v152, -|v35|
	v_max_f32_e32 v133, 0, v43
	v_add_f32_e32 v144, 1.0, v144
	v_log_f32_e32 v140, v142
	v_add_f32_e32 v83, v131, v130
	v_add_f32_e32 v80, v80, v81
	v_exp_f32_e64 v154, -|v34|
	v_max_f32_e32 v135, 0, v42
	v_add_f32_e32 v146, 1.0, v146
	v_log_f32_e32 v142, v144
	v_add_f32_e32 v130, v133, v132
	v_cndmask_b32_e64 v83, 0, v83, s[0:1]
	v_add_f32_e32 v82, v82, v80
	v_exp_f32_e64 v156, -|v33|
	v_max_f32_e32 v139, 0, v41
	v_add_f32_e32 v148, 1.0, v148
	v_log_f32_e32 v144, v146
	v_add_f32_e32 v131, v135, v134
	v_cndmask_b32_e64 v86, 0, v130, s[6:7]
	v_add_f32_e32 v83, v83, v82
	v_exp_f32_e64 v158, -|v32|
	v_max_f32_e32 v141, 0, v40
	v_add_f32_e32 v150, 1.0, v150
	v_log_f32_e32 v146, v148
	v_add_f32_e32 v132, v139, v137
	v_cndmask_b32_e64 v130, 0, v131, s[8:9]
	v_add_f32_e32 v86, v86, v83
	v_max_f32_e32 v143, 0, v39
	v_add_f32_e32 v152, 1.0, v152
	v_log_f32_e32 v148, v150
	v_add_f32_e32 v133, v141, v140
	v_cndmask_b32_e64 v131, 0, v132, s[10:11]
	v_add_f32_e32 v130, v130, v86
	v_max_f32_e32 v145, 0, v38
	v_add_f32_e32 v154, 1.0, v154
	v_log_f32_e32 v150, v152
	v_add_f32_e32 v134, v143, v142
	v_cndmask_b32_e64 v132, 0, v133, s[12:13]
	v_add_f32_e32 v131, v131, v130
	v_max_f32_e32 v147, 0, v37
	v_add_f32_e32 v156, 1.0, v156
	v_log_f32_e32 v152, v154
	v_add_f32_e32 v135, v145, v144
	v_cndmask_b32_e64 v133, 0, v134, s[14:15]
	v_add_f32_e32 v132, v132, v131
	v_max_f32_e32 v149, 0, v36
	v_add_f32_e32 v158, 1.0, v158
	v_log_f32_e32 v154, v156
	v_add_f32_e32 v137, v147, v146
	v_cndmask_b32_e64 v134, 0, v135, s[16:17]
	v_add_f32_e32 v133, v133, v132
	v_max_f32_e32 v151, 0, v35
	v_log_f32_e32 v156, v158
	v_add_f32_e32 v139, v149, v148
	v_cndmask_b32_e64 v135, 0, v137, s[20:21]
	v_add_f32_e32 v134, v134, v133
	v_max_f32_e32 v153, 0, v34
	v_add_f32_e32 v140, v151, v150
	v_cmp_lt_i32_e64 s[26:27], 3, v111
	v_cndmask_b32_e64 v137, 0, v139, s[24:25]
	v_add_f32_e32 v135, v135, v134
	v_max_f32_e32 v155, 0, v33
	v_add_f32_e32 v141, v153, v152
	v_cmp_lt_i32_e64 s[28:29], 2, v111
	v_cndmask_b32_e64 v139, 0, v140, s[26:27]
	v_add_f32_e32 v137, v137, v135
	v_max_f32_e32 v157, 0, v32
	v_add_f32_e32 v142, v155, v154
	v_cmp_lt_i32_e64 s[30:31], 1, v111
	v_cndmask_b32_e64 v140, 0, v141, s[28:29]
	v_add_f32_e32 v139, v139, v137
	v_add_f32_e32 v143, v157, v156
	v_cmp_lt_i32_e64 s[34:35], 0, v111
	v_cndmask_b32_e64 v141, 0, v142, s[30:31]
	v_add_f32_e32 v140, v140, v139
	v_cndmask_b32_e64 v142, 0, v143, s[34:35]
	v_add_f32_e32 v141, v141, v140
	v_add_f32_e32 v142, v142, v141
	ds_bpermute_b32 v143, v201, v142
	v_cmp_lt_i32_e32 vcc, 1, v111
	v_cmp_lt_i32_e64 s[0:1], 2, v111
	v_cmp_lt_i32_e64 s[6:7], 3, v111
	v_cmp_lt_i32_e64 s[8:9], 4, v111
	s_waitcnt lgkmcnt(0)
; #define MFMA32(a, b, c) __builtin_amdgcn_mfma_f32_32x32x16_bf16((a), (b), (c), 0, 0, 0)
;     static __device__ __forceinline__ bf16x8 vpack(const VRaw& x) { return pack8(x.v[0], x.v[1], x.v[2], x.v[3], x.v[4], x.v[5], x.v[6], x.v[7]); }
; template <class Src>
; __device__ __forceinline__ void sb_wave(const Src& src, const bf16* qrow, int kt_hi, int qpos, f32x16 (&O)[2]) {
;     ...
;         const float other = __shfl_xor(run, 32);
;         const float off = carry + (h == 0 ? other : 0.f);
;         float a[16];
; #pragma unroll
;         for (int i = 0; i < 16; ++i) { const bool valid = (kp0 + i) < qpos; a[i] = valid ? __builtin_amdgcn_exp2f(S[i] - (c[i] + off)) : 0.f; }
;         carry += run + other;
;         const bf16x8 pk0 = pack8(a[0], a[1], a[2], a[3], a[4], a[5], a[6], a[7]);
;         const bf16x8 pk1 = pack8(a[8], a[9], a[10], a[11], a[12], a[13], a[14], a[15]);
; #pragma unroll
;         for (int b = 0; b < 2; ++b) { O[b] = MFMA32(Src::vpack(vr[2 * b]), pk0, O[b]); O[b] = MFMA32(Src::vpack(vr[2 * b + 1]), pk1, O[b]); }
;         if (!__any(carry <= 150.0f)) break;
	v_cndmask_b32_e64 v144, 0, v143, s[4:5]
	v_add_f32_e32 v144, v99, v144
	v_add_f32_e32 v145, v144, v142
	v_add_f32_e32 v141, v144, v141
	v_add_f32_e32 v140, v144, v140
	v_add_f32_e32 v139, v144, v139
	v_add_f32_e32 v137, v144, v137
	v_add_f32_e32 v135, v144, v135
	v_add_f32_e32 v134, v144, v134
	v_add_f32_e32 v133, v144, v133
	v_sub_f32_e32 v32, v32, v145
	v_sub_f32_e32 v33, v33, v141
	v_sub_f32_e32 v34, v34, v140
	v_sub_f32_e32 v35, v35, v139
	v_sub_f32_e32 v36, v36, v137
	v_sub_f32_e32 v37, v37, v135
	v_sub_f32_e32 v38, v38, v134
	v_sub_f32_e32 v39, v39, v133
	v_exp_f32_e32 v32, v32
	v_exp_f32_e32 v33, v33
	v_exp_f32_e32 v34, v34
	v_exp_f32_e32 v35, v35
	v_exp_f32_e32 v36, v36
	v_exp_f32_e32 v37, v37
	v_exp_f32_e32 v38, v38
	v_exp_f32_e32 v39, v39
	v_cmp_lt_i32_e64 s[10:11], 5, v111
	v_cmp_lt_i32_e64 s[12:13], 6, v111
	v_cmp_lt_i32_e64 s[14:15], 7, v111
	v_cmp_lt_i32_e64 s[34:35], 0, v111
	v_cndmask_b32_e32 v33, 0, v33, vcc
	v_cndmask_b32_e64 v34, 0, v34, s[0:1]
	v_cndmask_b32_e64 v32, 0, v32, s[34:35]
	v_cndmask_b32_e64 v35, 0, v35, s[6:7]
	v_cndmask_b32_e64 v36, 0, v36, s[8:9]
	v_cndmask_b32_e64 v37, 0, v37, s[10:11]
	v_cndmask_b32_e64 v38, 0, v38, s[12:13]
	v_cndmask_b32_e64 v39, 0, v39, s[14:15]
	v_cvt_pk_bf16_f32 v32, v32, v33
	v_cvt_pk_bf16_f32 v33, v34, v35
	v_cvt_pk_bf16_f32 v34, v36, v37
	v_cvt_pk_bf16_f32 v35, v38, v39
	v_add_f32_e32 v132, v144, v132
	v_add_f32_e32 v131, v144, v131
	v_add_f32_e32 v130, v144, v130
	v_add_f32_e32 v86, v144, v86
	v_add_f32_e32 v83, v144, v83
	v_add_f32_e32 v82, v144, v82
	v_add_f32_e32 v80, v144, v80
	v_add_f32_e32 v81, v144, v81
	s_waitcnt vmcnt(3)
	v_mfma_f32_32x32x16_bf16 v[16:31], v[76:79], v[32:35], v[16:31]
	v_sub_f32_e32 v40, v40, v132
	v_sub_f32_e32 v41, v41, v131
	v_sub_f32_e32 v42, v42, v130
	v_sub_f32_e32 v43, v43, v86
	v_sub_f32_e32 v44, v44, v83
	v_sub_f32_e32 v45, v45, v82
	v_sub_f32_e32 v46, v46, v80
	s_waitcnt vmcnt(1)
	v_mfma_f32_32x32x16_bf16 v[0:15], v[72:75], v[32:35], v[0:15]
	v_sub_f32_e32 v47, v47, v81
	v_exp_f32_e32 v40, v40
	v_exp_f32_e32 v41, v41
	v_exp_f32_e32 v42, v42
	v_exp_f32_e32 v43, v43
	v_exp_f32_e32 v44, v44
	v_exp_f32_e32 v45, v45
	v_exp_f32_e32 v46, v46
	v_exp_f32_e32 v47, v47
	v_cmp_lt_i32_e64 s[16:17], 9, v111
	v_cmp_lt_i32_e64 s[20:21], 10, v111
	v_cmp_lt_i32_e64 s[24:25], 11, v111
	v_cmp_lt_i32_e64 s[26:27], 12, v111
	v_cmp_lt_i32_e64 s[28:29], 13, v111
	v_cmp_lt_i32_e64 s[30:31], 14, v111
	v_cmp_lt_i32_e32 vcc, 15, v111
	v_cmp_lt_i32_e64 s[0:1], 8, v111
	v_cndmask_b32_e64 v37, 0, v41, s[16:17]
	v_cndmask_b32_e64 v38, 0, v42, s[20:21]
	v_cndmask_b32_e64 v36, 0, v40, s[0:1]
	v_cndmask_b32_e64 v39, 0, v43, s[24:25]
	v_cndmask_b32_e64 v40, 0, v44, s[26:27]
	v_cndmask_b32_e64 v34, 0, v45, s[28:29]
	v_cndmask_b32_e64 v35, 0, v46, s[30:31]
	v_cndmask_b32_e32 v41, 0, v47, vcc
	v_cvt_pk_bf16_f32 v32, v36, v37
	v_cvt_pk_bf16_f32 v33, v38, v39
	v_cvt_pk_bf16_f32 v34, v40, v34
	v_cvt_pk_bf16_f32 v35, v35, v41
	v_add_f32_e32 v36, v142, v143
	v_add_f32_e32 v99, v99, v36
	v_mfma_f32_32x32x16_bf16 v[16:31], v[68:71], v[32:35], v[16:31]
	v_cmp_ge_f32_e64 s[0:1], s74, v99
	s_cmp_lg_u64 s[0:1], 0
	v_add_co_u32_e32 v110, vcc, -1, v110
	s_cselect_b64 s[0:1], -1, 0
	s_and_b64 s[0:1], vcc, s[0:1]
	v_add_u32_e32 v111, 32, v111
	s_waitcnt vmcnt(0)
	v_mfma_f32_32x32x16_bf16 v[0:15], v[64:67], v[32:35], v[0:15]
	s_sub_i32 s39, s39, 32
	s_and_b64 vcc, exec, s[0:1]
	s_cbranch_vccnz .LBB0_533
	s_mov_b64 s[0:1], -1
	s_branch .LBB0_539
